# P0 x->bf16 copy with row sums: all 32 row loads of a wave in flight, counted waits, the eight wave reductions interleaved (the compiler's loop waited vmcnt(0) after every load)
# speedup vs baseline: 1.0010x; 1.0007x over previous
; __device__ __forceinline__ unsigned cvt_pk_bf16(float lo, float hi) { f32x2_t v = {lo, hi}; bf16x2_t b = __builtin_convertvector(v, bf16x2_t); return __builtin_bit_cast(unsigned, b); }
; #define GAS __attribute__((address_space(1)))
; __device__ __forceinline__ void p0_prologue(Frame& F, const In& I, unsigned char* ws) {
;     ...
;     for (int m0 = 8 * gw; m0 < M; m0 += 8 * NGW) {
;         float keep = 0.f;
; #pragma unroll 4
;         for (int j = 0; j < 8; ++j) { const int m = m0 + j;
;             const GAS f32x4* xr = (const GAS f32x4*)(I.x + (size_t)m * D) + F.lane; GAS unsigned long long* o8 = (GAS unsigned long long*)(HB + (size_t)m * D) + F.lane; float s = 0.f;
; #pragma unroll
;             for (int jj = 0; jj < 4; ++jj) { const f32x4 v = xr[64 * jj]; s += (v.x * v.x + v.y * v.y) + (v.z * v.z + v.w * v.w);
;                 o8[64 * jj] = (unsigned long long)pg8::cvt_pk_bf16(v.x, v.y) | ((unsigned long long)pg8::cvt_pk_bf16(v.z, v.w) << 32); }
;             s = wave_sum(s);
;             if (F.lane == j) keep = s; }
; #pragma unroll
;         for (int pp = 0; pp < 2; ++pp) { const int p = 8 * pp + (F.lane >> 3); ssq[(size_t)p * M + m0 + (F.lane & 7)] = (p == 0) ? keep : 0.f; }
.LBB0_39:
	s_add_i32 s20, s8, 0
	s_ashr_i32 s21, s20, 31
	s_lshl_b64 s[22:23], s[20:21], 12
	v_lshl_add_u64 v[16:17], v[56:57], 0, s[22:23]
	s_lshl_b64 s[22:23], s[20:21], 11
	v_lshl_add_u64 v[32:33], v[52:53], 0, s[22:23]
	s_add_i32 s20, s8, 1
	s_ashr_i32 s21, s20, 31
	s_lshl_b64 s[22:23], s[20:21], 12
	v_lshl_add_u64 v[18:19], v[56:57], 0, s[22:23]
	s_lshl_b64 s[22:23], s[20:21], 11
	v_lshl_add_u64 v[34:35], v[52:53], 0, s[22:23]
	s_add_i32 s20, s8, 2
	s_ashr_i32 s21, s20, 31
	s_lshl_b64 s[22:23], s[20:21], 12
	v_lshl_add_u64 v[20:21], v[56:57], 0, s[22:23]
	s_lshl_b64 s[22:23], s[20:21], 11
	v_lshl_add_u64 v[36:37], v[52:53], 0, s[22:23]
	s_add_i32 s20, s8, 3
	s_ashr_i32 s21, s20, 31
	s_lshl_b64 s[22:23], s[20:21], 12
	v_lshl_add_u64 v[22:23], v[56:57], 0, s[22:23]
	s_lshl_b64 s[22:23], s[20:21], 11
	v_lshl_add_u64 v[38:39], v[52:53], 0, s[22:23]
	s_add_i32 s20, s8, 4
	s_ashr_i32 s21, s20, 31
	s_lshl_b64 s[22:23], s[20:21], 12
	v_lshl_add_u64 v[24:25], v[56:57], 0, s[22:23]
	s_lshl_b64 s[22:23], s[20:21], 11
	v_lshl_add_u64 v[40:41], v[52:53], 0, s[22:23]
	s_add_i32 s20, s8, 5
	s_ashr_i32 s21, s20, 31
	s_lshl_b64 s[22:23], s[20:21], 12
	v_lshl_add_u64 v[26:27], v[56:57], 0, s[22:23]
	s_lshl_b64 s[22:23], s[20:21], 11
	v_lshl_add_u64 v[42:43], v[52:53], 0, s[22:23]
	s_add_i32 s20, s8, 6
	s_ashr_i32 s21, s20, 31
	s_lshl_b64 s[22:23], s[20:21], 12
	v_lshl_add_u64 v[28:29], v[56:57], 0, s[22:23]
	s_lshl_b64 s[22:23], s[20:21], 11
	v_lshl_add_u64 v[44:45], v[52:53], 0, s[22:23]
	s_add_i32 s20, s8, 7
	s_ashr_i32 s21, s20, 31
	s_lshl_b64 s[22:23], s[20:21], 12
	v_lshl_add_u64 v[30:31], v[56:57], 0, s[22:23]
	s_lshl_b64 s[22:23], s[20:21], 11
	v_lshl_add_u64 v[46:47], v[52:53], 0, s[22:23]
	global_load_dwordx4 v[88:91], v[16:17], off
	global_load_dwordx4 v[92:95], v[16:17], off offset:1024
	global_load_dwordx4 v[96:99], v[16:17], off offset:2048
	global_load_dwordx4 v[100:103], v[16:17], off offset:3072
	global_load_dwordx4 v[104:107], v[18:19], off
	global_load_dwordx4 v[108:111], v[18:19], off offset:1024
	global_load_dwordx4 v[112:115], v[18:19], off offset:2048
	global_load_dwordx4 v[116:119], v[18:19], off offset:3072
	global_load_dwordx4 v[120:123], v[20:21], off
	global_load_dwordx4 v[124:127], v[20:21], off offset:1024
	global_load_dwordx4 v[128:131], v[20:21], off offset:2048
	global_load_dwordx4 v[132:135], v[20:21], off offset:3072
	global_load_dwordx4 v[136:139], v[22:23], off
	global_load_dwordx4 v[140:143], v[22:23], off offset:1024
	global_load_dwordx4 v[144:147], v[22:23], off offset:2048
	global_load_dwordx4 v[148:151], v[22:23], off offset:3072
	global_load_dwordx4 v[152:155], v[24:25], off
	global_load_dwordx4 v[156:159], v[24:25], off offset:1024
	global_load_dwordx4 v[160:163], v[24:25], off offset:2048
	global_load_dwordx4 v[164:167], v[24:25], off offset:3072
	global_load_dwordx4 v[168:171], v[26:27], off
	global_load_dwordx4 v[172:175], v[26:27], off offset:1024
	global_load_dwordx4 v[176:179], v[26:27], off offset:2048
	global_load_dwordx4 v[180:183], v[26:27], off offset:3072
	global_load_dwordx4 v[184:187], v[28:29], off
	global_load_dwordx4 v[188:191], v[28:29], off offset:1024
	global_load_dwordx4 v[192:195], v[28:29], off offset:2048
	global_load_dwordx4 v[196:199], v[28:29], off offset:3072
	global_load_dwordx4 v[200:203], v[30:31], off
	global_load_dwordx4 v[204:207], v[30:31], off offset:1024
	global_load_dwordx4 v[208:211], v[30:31], off offset:2048
	global_load_dwordx4 v[212:215], v[30:31], off offset:3072
	s_waitcnt vmcnt(28)
	v_cvt_pk_bf16_f32 v2, v88, v89
	v_cvt_pk_bf16_f32 v3, v90, v91
	global_store_dwordx2 v[32:33], v[2:3], off
	v_cvt_pk_bf16_f32 v4, v92, v93
	v_cvt_pk_bf16_f32 v5, v94, v95
	global_store_dwordx2 v[32:33], v[4:5], off offset:512
	v_cvt_pk_bf16_f32 v2, v96, v97
	v_cvt_pk_bf16_f32 v3, v98, v99
	global_store_dwordx2 v[32:33], v[2:3], off offset:1024
	v_cvt_pk_bf16_f32 v4, v100, v101
	v_cvt_pk_bf16_f32 v5, v102, v103
	global_store_dwordx2 v[32:33], v[4:5], off offset:1536
	v_pk_mul_f32 v[14:15], v[88:89], v[88:89]
	v_pk_fma_f32 v[14:15], v[90:91], v[90:91], v[14:15]
	v_pk_fma_f32 v[14:15], v[92:93], v[92:93], v[14:15]
	v_pk_fma_f32 v[14:15], v[94:95], v[94:95], v[14:15]
	v_pk_fma_f32 v[14:15], v[96:97], v[96:97], v[14:15]
	v_pk_fma_f32 v[14:15], v[98:99], v[98:99], v[14:15]
	v_pk_fma_f32 v[14:15], v[100:101], v[100:101], v[14:15]
	v_pk_fma_f32 v[14:15], v[102:103], v[102:103], v[14:15]
	v_add_f32_e32 v6, v14, v15
	s_waitcnt vmcnt(28)
	v_cvt_pk_bf16_f32 v2, v104, v105
	v_cvt_pk_bf16_f32 v3, v106, v107
	global_store_dwordx2 v[34:35], v[2:3], off
	v_cvt_pk_bf16_f32 v4, v108, v109
	v_cvt_pk_bf16_f32 v5, v110, v111
	global_store_dwordx2 v[34:35], v[4:5], off offset:512
	v_cvt_pk_bf16_f32 v2, v112, v113
	v_cvt_pk_bf16_f32 v3, v114, v115
	global_store_dwordx2 v[34:35], v[2:3], off offset:1024
	v_cvt_pk_bf16_f32 v4, v116, v117
	v_cvt_pk_bf16_f32 v5, v118, v119
	global_store_dwordx2 v[34:35], v[4:5], off offset:1536
	v_pk_mul_f32 v[14:15], v[104:105], v[104:105]
	v_pk_fma_f32 v[14:15], v[106:107], v[106:107], v[14:15]
	v_pk_fma_f32 v[14:15], v[108:109], v[108:109], v[14:15]
	v_pk_fma_f32 v[14:15], v[110:111], v[110:111], v[14:15]
	v_pk_fma_f32 v[14:15], v[112:113], v[112:113], v[14:15]
	v_pk_fma_f32 v[14:15], v[114:115], v[114:115], v[14:15]
	v_pk_fma_f32 v[14:15], v[116:117], v[116:117], v[14:15]
	v_pk_fma_f32 v[14:15], v[118:119], v[118:119], v[14:15]
	v_add_f32_e32 v7, v14, v15
	s_waitcnt vmcnt(28)
; __device__ __forceinline__ unsigned cvt_pk_bf16(float lo, float hi) { f32x2_t v = {lo, hi}; bf16x2_t b = __builtin_convertvector(v, bf16x2_t); return __builtin_bit_cast(unsigned, b); }
; #define GAS __attribute__((address_space(1)))
; __device__ __forceinline__ void p0_prologue(Frame& F, const In& I, unsigned char* ws) {
;     ...
;         for (int j = 0; j < 8; ++j) { const int m = m0 + j;
;             const GAS f32x4* xr = (const GAS f32x4*)(I.x + (size_t)m * D) + F.lane; GAS unsigned long long* o8 = (GAS unsigned long long*)(HB + (size_t)m * D) + F.lane; float s = 0.f;
; #pragma unroll
;             for (int jj = 0; jj < 4; ++jj) { const f32x4 v = xr[64 * jj]; s += (v.x * v.x + v.y * v.y) + (v.z * v.z + v.w * v.w);
;                 o8[64 * jj] = (unsigned long long)pg8::cvt_pk_bf16(v.x, v.y) | ((unsigned long long)pg8::cvt_pk_bf16(v.z, v.w) << 32); }
;             s = wave_sum(s);
;             if (F.lane == j) keep = s; }
	v_cvt_pk_bf16_f32 v2, v120, v121
	v_cvt_pk_bf16_f32 v3, v122, v123
	global_store_dwordx2 v[36:37], v[2:3], off
	v_cvt_pk_bf16_f32 v4, v124, v125
	v_cvt_pk_bf16_f32 v5, v126, v127
	global_store_dwordx2 v[36:37], v[4:5], off offset:512
	v_cvt_pk_bf16_f32 v2, v128, v129
	v_cvt_pk_bf16_f32 v3, v130, v131
	global_store_dwordx2 v[36:37], v[2:3], off offset:1024
	v_cvt_pk_bf16_f32 v4, v132, v133
	v_cvt_pk_bf16_f32 v5, v134, v135
	global_store_dwordx2 v[36:37], v[4:5], off offset:1536
	v_pk_mul_f32 v[14:15], v[120:121], v[120:121]
	v_pk_fma_f32 v[14:15], v[122:123], v[122:123], v[14:15]
	v_pk_fma_f32 v[14:15], v[124:125], v[124:125], v[14:15]
	v_pk_fma_f32 v[14:15], v[126:127], v[126:127], v[14:15]
	v_pk_fma_f32 v[14:15], v[128:129], v[128:129], v[14:15]
	v_pk_fma_f32 v[14:15], v[130:131], v[130:131], v[14:15]
	v_pk_fma_f32 v[14:15], v[132:133], v[132:133], v[14:15]
	v_pk_fma_f32 v[14:15], v[134:135], v[134:135], v[14:15]
	v_add_f32_e32 v8, v14, v15
	s_waitcnt vmcnt(28)
	v_cvt_pk_bf16_f32 v2, v136, v137
	v_cvt_pk_bf16_f32 v3, v138, v139
	global_store_dwordx2 v[38:39], v[2:3], off
	v_cvt_pk_bf16_f32 v4, v140, v141
	v_cvt_pk_bf16_f32 v5, v142, v143
	global_store_dwordx2 v[38:39], v[4:5], off offset:512
	v_cvt_pk_bf16_f32 v2, v144, v145
	v_cvt_pk_bf16_f32 v3, v146, v147
	global_store_dwordx2 v[38:39], v[2:3], off offset:1024
	v_cvt_pk_bf16_f32 v4, v148, v149
	v_cvt_pk_bf16_f32 v5, v150, v151
	global_store_dwordx2 v[38:39], v[4:5], off offset:1536
	v_pk_mul_f32 v[14:15], v[136:137], v[136:137]
	v_pk_fma_f32 v[14:15], v[138:139], v[138:139], v[14:15]
	v_pk_fma_f32 v[14:15], v[140:141], v[140:141], v[14:15]
	v_pk_fma_f32 v[14:15], v[142:143], v[142:143], v[14:15]
	v_pk_fma_f32 v[14:15], v[144:145], v[144:145], v[14:15]
	v_pk_fma_f32 v[14:15], v[146:147], v[146:147], v[14:15]
	v_pk_fma_f32 v[14:15], v[148:149], v[148:149], v[14:15]
	v_pk_fma_f32 v[14:15], v[150:151], v[150:151], v[14:15]
	v_add_f32_e32 v9, v14, v15
	s_waitcnt vmcnt(28)
	v_cvt_pk_bf16_f32 v2, v152, v153
	v_cvt_pk_bf16_f32 v3, v154, v155
	global_store_dwordx2 v[40:41], v[2:3], off
	v_cvt_pk_bf16_f32 v4, v156, v157
	v_cvt_pk_bf16_f32 v5, v158, v159
	global_store_dwordx2 v[40:41], v[4:5], off offset:512
	v_cvt_pk_bf16_f32 v2, v160, v161
	v_cvt_pk_bf16_f32 v3, v162, v163
	global_store_dwordx2 v[40:41], v[2:3], off offset:1024
	v_cvt_pk_bf16_f32 v4, v164, v165
	v_cvt_pk_bf16_f32 v5, v166, v167
	global_store_dwordx2 v[40:41], v[4:5], off offset:1536
	v_pk_mul_f32 v[14:15], v[152:153], v[152:153]
	v_pk_fma_f32 v[14:15], v[154:155], v[154:155], v[14:15]
	v_pk_fma_f32 v[14:15], v[156:157], v[156:157], v[14:15]
	v_pk_fma_f32 v[14:15], v[158:159], v[158:159], v[14:15]
	v_pk_fma_f32 v[14:15], v[160:161], v[160:161], v[14:15]
	v_pk_fma_f32 v[14:15], v[162:163], v[162:163], v[14:15]
	v_pk_fma_f32 v[14:15], v[164:165], v[164:165], v[14:15]
	v_pk_fma_f32 v[14:15], v[166:167], v[166:167], v[14:15]
	v_add_f32_e32 v10, v14, v15
	s_waitcnt vmcnt(28)
	v_cvt_pk_bf16_f32 v2, v168, v169
	v_cvt_pk_bf16_f32 v3, v170, v171
	global_store_dwordx2 v[42:43], v[2:3], off
	v_cvt_pk_bf16_f32 v4, v172, v173
	v_cvt_pk_bf16_f32 v5, v174, v175
	global_store_dwordx2 v[42:43], v[4:5], off offset:512
	v_cvt_pk_bf16_f32 v2, v176, v177
	v_cvt_pk_bf16_f32 v3, v178, v179
	global_store_dwordx2 v[42:43], v[2:3], off offset:1024
	v_cvt_pk_bf16_f32 v4, v180, v181
	v_cvt_pk_bf16_f32 v5, v182, v183
	global_store_dwordx2 v[42:43], v[4:5], off offset:1536
	v_pk_mul_f32 v[14:15], v[168:169], v[168:169]
	v_pk_fma_f32 v[14:15], v[170:171], v[170:171], v[14:15]
	v_pk_fma_f32 v[14:15], v[172:173], v[172:173], v[14:15]
	v_pk_fma_f32 v[14:15], v[174:175], v[174:175], v[14:15]
	v_pk_fma_f32 v[14:15], v[176:177], v[176:177], v[14:15]
	v_pk_fma_f32 v[14:15], v[178:179], v[178:179], v[14:15]
	v_pk_fma_f32 v[14:15], v[180:181], v[180:181], v[14:15]
	v_pk_fma_f32 v[14:15], v[182:183], v[182:183], v[14:15]
	v_add_f32_e32 v11, v14, v15
	s_waitcnt vmcnt(28)
	v_cvt_pk_bf16_f32 v2, v184, v185
	v_cvt_pk_bf16_f32 v3, v186, v187
	global_store_dwordx2 v[44:45], v[2:3], off
	v_cvt_pk_bf16_f32 v4, v188, v189
	v_cvt_pk_bf16_f32 v5, v190, v191
	global_store_dwordx2 v[44:45], v[4:5], off offset:512
	v_cvt_pk_bf16_f32 v2, v192, v193
	v_cvt_pk_bf16_f32 v3, v194, v195
	global_store_dwordx2 v[44:45], v[2:3], off offset:1024
	v_cvt_pk_bf16_f32 v4, v196, v197
	v_cvt_pk_bf16_f32 v5, v198, v199
	global_store_dwordx2 v[44:45], v[4:5], off offset:1536
	v_pk_mul_f32 v[14:15], v[184:185], v[184:185]
	v_pk_fma_f32 v[14:15], v[186:187], v[186:187], v[14:15]
	v_pk_fma_f32 v[14:15], v[188:189], v[188:189], v[14:15]
	v_pk_fma_f32 v[14:15], v[190:191], v[190:191], v[14:15]
	v_pk_fma_f32 v[14:15], v[192:193], v[192:193], v[14:15]
	v_pk_fma_f32 v[14:15], v[194:195], v[194:195], v[14:15]
	v_pk_fma_f32 v[14:15], v[196:197], v[196:197], v[14:15]
	v_pk_fma_f32 v[14:15], v[198:199], v[198:199], v[14:15]
	v_add_f32_e32 v12, v14, v15
	s_waitcnt vmcnt(28)
; __device__ __forceinline__ unsigned cvt_pk_bf16(float lo, float hi) { f32x2_t v = {lo, hi}; bf16x2_t b = __builtin_convertvector(v, bf16x2_t); return __builtin_bit_cast(unsigned, b); }
; #define GAS __attribute__((address_space(1)))
; __device__ __forceinline__ void p0_prologue(Frame& F, const In& I, unsigned char* ws) {
;     ...
;         for (int j = 0; j < 8; ++j) { const int m = m0 + j;
;             const GAS f32x4* xr = (const GAS f32x4*)(I.x + (size_t)m * D) + F.lane; GAS unsigned long long* o8 = (GAS unsigned long long*)(HB + (size_t)m * D) + F.lane; float s = 0.f;
; #pragma unroll
;             for (int jj = 0; jj < 4; ++jj) { const f32x4 v = xr[64 * jj]; s += (v.x * v.x + v.y * v.y) + (v.z * v.z + v.w * v.w);
;                 o8[64 * jj] = (unsigned long long)pg8::cvt_pk_bf16(v.x, v.y) | ((unsigned long long)pg8::cvt_pk_bf16(v.z, v.w) << 32); }
;             s = wave_sum(s);
;             if (F.lane == j) keep = s; }
; #pragma unroll
;         for (int pp = 0; pp < 2; ++pp) { const int p = 8 * pp + (F.lane >> 3); ssq[(size_t)p * M + m0 + (F.lane & 7)] = (p == 0) ? keep : 0.f; }
	v_cvt_pk_bf16_f32 v2, v200, v201
	v_cvt_pk_bf16_f32 v3, v202, v203
	global_store_dwordx2 v[46:47], v[2:3], off
	v_cvt_pk_bf16_f32 v4, v204, v205
	v_cvt_pk_bf16_f32 v5, v206, v207
	global_store_dwordx2 v[46:47], v[4:5], off offset:512
	v_cvt_pk_bf16_f32 v2, v208, v209
	v_cvt_pk_bf16_f32 v3, v210, v211
	global_store_dwordx2 v[46:47], v[2:3], off offset:1024
	v_cvt_pk_bf16_f32 v4, v212, v213
	v_cvt_pk_bf16_f32 v5, v214, v215
	global_store_dwordx2 v[46:47], v[4:5], off offset:1536
	v_pk_mul_f32 v[14:15], v[200:201], v[200:201]
	v_pk_fma_f32 v[14:15], v[202:203], v[202:203], v[14:15]
	v_pk_fma_f32 v[14:15], v[204:205], v[204:205], v[14:15]
	v_pk_fma_f32 v[14:15], v[206:207], v[206:207], v[14:15]
	v_pk_fma_f32 v[14:15], v[208:209], v[208:209], v[14:15]
	v_pk_fma_f32 v[14:15], v[210:211], v[210:211], v[14:15]
	v_pk_fma_f32 v[14:15], v[212:213], v[212:213], v[14:15]
	v_pk_fma_f32 v[14:15], v[214:215], v[214:215], v[14:15]
	v_add_f32_e32 v13, v14, v15
	ds_bpermute_b32 v76, v69, v6
	ds_bpermute_b32 v77, v69, v7
	ds_bpermute_b32 v78, v69, v8
	ds_bpermute_b32 v79, v69, v9
	ds_bpermute_b32 v80, v69, v10
	ds_bpermute_b32 v81, v69, v11
	ds_bpermute_b32 v82, v69, v12
	ds_bpermute_b32 v83, v69, v13
	s_waitcnt lgkmcnt(0)
	v_add_f32_e32 v6, v6, v76
	v_add_f32_e32 v7, v7, v77
	v_add_f32_e32 v8, v8, v78
	v_add_f32_e32 v9, v9, v79
	v_add_f32_e32 v10, v10, v80
	v_add_f32_e32 v11, v11, v81
	v_add_f32_e32 v12, v12, v82
	v_add_f32_e32 v13, v13, v83
	ds_bpermute_b32 v76, v70, v6
	ds_bpermute_b32 v77, v70, v7
	ds_bpermute_b32 v78, v70, v8
	ds_bpermute_b32 v79, v70, v9
	ds_bpermute_b32 v80, v70, v10
	ds_bpermute_b32 v81, v70, v11
	ds_bpermute_b32 v82, v70, v12
	ds_bpermute_b32 v83, v70, v13
	s_waitcnt lgkmcnt(0)
	v_add_f32_e32 v6, v6, v76
	v_add_f32_e32 v7, v7, v77
	v_add_f32_e32 v8, v8, v78
	v_add_f32_e32 v9, v9, v79
	v_add_f32_e32 v10, v10, v80
	v_add_f32_e32 v11, v11, v81
	v_add_f32_e32 v12, v12, v82
	v_add_f32_e32 v13, v13, v83
	ds_bpermute_b32 v76, v71, v6
	ds_bpermute_b32 v77, v71, v7
	ds_bpermute_b32 v78, v71, v8
	ds_bpermute_b32 v79, v71, v9
	ds_bpermute_b32 v80, v71, v10
	ds_bpermute_b32 v81, v71, v11
	ds_bpermute_b32 v82, v71, v12
	ds_bpermute_b32 v83, v71, v13
	s_waitcnt lgkmcnt(0)
	v_add_f32_e32 v6, v6, v76
	v_add_f32_e32 v7, v7, v77
	v_add_f32_e32 v8, v8, v78
	v_add_f32_e32 v9, v9, v79
	v_add_f32_e32 v10, v10, v80
	v_add_f32_e32 v11, v11, v81
	v_add_f32_e32 v12, v12, v82
	v_add_f32_e32 v13, v13, v83
	ds_bpermute_b32 v76, v72, v6
	ds_bpermute_b32 v77, v72, v7
	ds_bpermute_b32 v78, v72, v8
	ds_bpermute_b32 v79, v72, v9
	ds_bpermute_b32 v80, v72, v10
	ds_bpermute_b32 v81, v72, v11
	ds_bpermute_b32 v82, v72, v12
	ds_bpermute_b32 v83, v72, v13
	s_waitcnt lgkmcnt(0)
	v_add_f32_e32 v6, v6, v76
	v_add_f32_e32 v7, v7, v77
	v_add_f32_e32 v8, v8, v78
	v_add_f32_e32 v9, v9, v79
	v_add_f32_e32 v10, v10, v80
	v_add_f32_e32 v11, v11, v81
	v_add_f32_e32 v12, v12, v82
	v_add_f32_e32 v13, v13, v83
	ds_bpermute_b32 v76, v73, v6
	ds_bpermute_b32 v77, v73, v7
	ds_bpermute_b32 v78, v73, v8
	ds_bpermute_b32 v79, v73, v9
	ds_bpermute_b32 v80, v73, v10
	ds_bpermute_b32 v81, v73, v11
	ds_bpermute_b32 v82, v73, v12
	ds_bpermute_b32 v83, v73, v13
	s_waitcnt lgkmcnt(0)
	v_add_f32_e32 v6, v6, v76
	v_add_f32_e32 v7, v7, v77
	v_add_f32_e32 v8, v8, v78
	v_add_f32_e32 v9, v9, v79
	v_add_f32_e32 v10, v10, v80
	v_add_f32_e32 v11, v11, v81
	v_add_f32_e32 v12, v12, v82
	v_add_f32_e32 v13, v13, v83
	ds_bpermute_b32 v76, v74, v6
	ds_bpermute_b32 v77, v74, v7
	ds_bpermute_b32 v78, v74, v8
	ds_bpermute_b32 v79, v74, v9
	ds_bpermute_b32 v80, v74, v10
	ds_bpermute_b32 v81, v74, v11
	ds_bpermute_b32 v82, v74, v12
	ds_bpermute_b32 v83, v74, v13
	s_waitcnt lgkmcnt(0)
	v_add_f32_e32 v6, v6, v76
	v_add_f32_e32 v7, v7, v77
	v_add_f32_e32 v8, v8, v78
	v_add_f32_e32 v9, v9, v79
	v_add_f32_e32 v10, v10, v80
	v_add_f32_e32 v11, v11, v81
	v_add_f32_e32 v12, v12, v82
	v_add_f32_e32 v13, v13, v83
	v_cmp_eq_u32_e32 vcc, 0, v68
	s_nop 1
	v_cndmask_b32_e32 v50, v50, v6, vcc
	v_cmp_eq_u32_e32 vcc, 1, v68
	s_nop 1
	v_cndmask_b32_e32 v50, v50, v7, vcc
	v_cmp_eq_u32_e32 vcc, 2, v68
	s_nop 1
	v_cndmask_b32_e32 v50, v50, v8, vcc
	v_cmp_eq_u32_e32 vcc, 3, v68
	s_nop 1
	v_cndmask_b32_e32 v50, v50, v9, vcc
	v_cmp_eq_u32_e32 vcc, 4, v68
	s_nop 1
	v_cndmask_b32_e32 v50, v50, v10, vcc
	v_cmp_eq_u32_e32 vcc, 5, v68
	s_nop 1
	v_cndmask_b32_e32 v50, v50, v11, vcc
	v_cmp_eq_u32_e32 vcc, 6, v68
	s_nop 1
	v_cndmask_b32_e32 v50, v50, v12, vcc
	v_cmp_eq_u32_e32 vcc, 7, v68
	s_nop 1
	v_cndmask_b32_e32 v50, v50, v13, vcc
	s_mov_b32 s2, 8
	s_ashr_i32 s9, s8, 31
	v_cndmask_b32_e64 v4, 0, v50, s[4:5]
	v_lshl_add_u64 v[2:3], s[8:9], 2, v[54:55]
	global_store_dword v[2:3], v4, off
	v_add_co_u32_e32 v2, vcc, 0x80000, v2
	s_add_i32 s8, s8, s10
	s_nop 0
	v_addc_co_u32_e32 v3, vcc, 0, v3, vcc
	v_lshl_add_u64 v[58:59], v[58:59], 0, s[12:13]
	s_cmpk_gt_i32 s8, 0x3fff
	v_lshl_add_u64 v[60:61], v[60:61], 0, s[14:15]
	global_store_dword v[2:3], v51, off
	s_cbranch_scc0 .LBB0_38
